# input-projection seam: one early-arriving workgroup per XCD writes the L2 back before it arrives
# speedup vs baseline: 1.0048x; 1.0048x over previous
; __device__ __forceinline__ unsigned xb_add(unsigned* p, unsigned v) { return __hip_atomic_fetch_add(p, v, __ATOMIC_RELAXED, __HIP_MEMORY_SCOPE_AGENT); }
; __device__ __forceinline__ void xcd_barrier(const XcdBarrier& b) {
;     asm volatile("s_waitcnt vmcnt(0)" ::: "memory");
;     __syncthreads();
;     if (threadIdx.x == 0) {
;         unsigned* bar = b.bar;
;         __builtin_amdgcn_s_waitcnt(0);
;         unsigned nloc = b.st[0], nx = b.st[1];
;         if (nloc == 0u) { xcd_barrier_complete(bar, b.x, nloc, nx); b.st[0] = nloc; b.st[1] = nx; }
;         const unsigned old = xb_add(&bar[XB_XSUB(b.x)], 1u);
;         const unsigned gen = old / nloc;
;         if (old + 1u == (gen + 1u) * nloc) {
;             __builtin_amdgcn_fence(__ATOMIC_RELEASE, "agent");
;             asm volatile("s_waitcnt vmcnt(0)" ::: "memory");
;             const unsigned og = xb_add(&bar[XB_TOP], 1u);
;             const unsigned tg = og / nx;
;             if (og + 1u == (tg + 1u) * nx) xb_add(&bar[XB_TOPGEN], 1u);
.Lin_seam:
	s_lshr_b32 s4, s2, 3
	s_cmp_lg_u32 s4, 31
	s_cbranch_scc1 .Lpf_skip
	buffer_wbl2 sc1
